# prompt attention tasks: gate rows and outputs move as whole rows through a per-wave LDS tile
# baseline (speedup 1.0000x reference)
; __device__ __forceinline__ unsigned f2bf(float f) { return pk2(f, 0.f) & 0xffffu; }
; __device__ __forceinline__ float siluf_(float x) { return x * __builtin_amdgcn_rcpf(1.f + __expf(-x)); }
; __device__ __forceinline__ void attn_prompt_item(const Args& A, LAS unsigned char* lds, int tid, int lane, int wave, int b, int nb, int kvh) {
;     ...
;         unsigned short gts[2][4][4];
; #pragma unroll
;         for (int mt = 0; mt < 2; ++mt)
; #pragma unroll
;             for (int j = 0; j < 4; ++j) { const size_t row = (size_t)b * SEQ + nb * 128 + tt * 32 + mt * 16 + q4 * 4 + j;
; #pragma unroll
;                 for (int dt = 0; dt < 4; ++dt) gts[mt][j][dt] = Z[row * NZ + O_GA + hq * 64 + dt * 16 + fr]; }
;     ...
; #pragma unroll
;         for (int mt = 0; mt < 2; ++mt)
; #pragma unroll
;             for (int j = 0; j < 4; ++j) {
;                 const int tq = tt * 32 + mt * 16 + q4 * 4 + j; const size_t row = (size_t)b * SEQ + nb * 128 + tq; const float il = __builtin_amdgcn_rcpf(lrow[mt][j]);
; #pragma unroll
;                 for (int dt = 0; dt < 4; ++dt) { const int d = dt * 16 + fr; const float g = bf2f(gts[mt][j][dt]);
;                     MIX[row * DM + 512 + hq * 64 + d] = (bf16_t)f2bf(O[mt][dt][j] * il * siluf_(g)); }
.Lpst_noout3:
	s_add_i32 s23, s10, s22
	s_mul_i32 s98, s23, 0x1c00
	s_mul_hi_u32 s99, s23, 0x1c00
	s_add_u32 s98, s98, s94
	s_addc_u32 s99, s99, s95
	s_lshl_b32 s59, s21, 9
	s_add_i32 s78, s59, 0x1700
	s_add_u32 s98, s98, s78
	s_addc_u32 s99, s99, 0
	s_lshl_b32 s78, s23, 11
	s_add_u32 s100, s96, 0xe00000
	s_addc_u32 s101, s97, 0
	s_add_u32 s100, s100, s78
	s_addc_u32 s101, s101, 0
	s_add_i32 s59, s59, 0x400
	s_add_u32 s100, s100, s59
	s_addc_u32 s101, s101, 0
	v_bfe_u32 v240, v144, 6, 2
	v_lshlrev_b32_e32 v240, 5, v240
	v_bfe_u32 v241, v144, 3, 3
	v_add_u32_e32 v240, v240, v241
	v_and_b32_e32 v242, 7, v144
	v_lshlrev_b32_e32 v242, 4, v242
	v_mul_u32_u24_e32 v236, 0x1c00, v240
	v_add_u32_e32 v236, v236, v242
	v_lshl_add_u32 v237, v240, 11, v242
	v_lshrrev_b32_e32 v240, 6, v144
	v_mul_u32_u24_e32 v240, 0x1200, v240
	v_add_u32_e32 v240, 0x15c00, v240
	v_mul_u32_u24_e32 v238, 0x90, v241
	v_add3_u32 v238, v238, v242, v240
	v_bfe_u32 v241, v144, 4, 2
	v_mul_u32_u24_e32 v239, 0x240, v241
	v_and_b32_e32 v242, 15, v144
	v_lshl_add_u32 v239, v242, 1, v239
	v_add_u32_e32 v239, v239, v240

; __device__ __forceinline__ void unpack8(u32x4 u, float* f) { f[0] = bflo(u.x); f[1] = bfhi(u.x); f[2] = bflo(u.y); f[3] = bfhi(u.y); f[4] = bflo(u.z); f[5] = bfhi(u.z); f[6] = bflo(u.w); f[7] = bfhi(u.w); }
; __device__ __forceinline__ u32x4 pack8(const float* f) { u32x4 o; o.x = pk2(f[0], f[1]); o.y = pk2(f[2], f[3]); o.z = pk2(f[4], f[5]); o.w = pk2(f[6], f[7]); return o; }
; __device__ __forceinline__ void attn_prompt_item(const Args& A, LAS unsigned char* lds, int tid, int lane, int wave, int b, int nb, int kvh) {
;     ...
;     for (int task = wave; task < 16; task += 8) {
;         const int g = task >> 2, tt = task & 3, hq = kvh * 4 + g;
;         const float sink = A.sinks[hq] * 1.4426950408889634f;
;         bf16x8 Qf[2][2];
; #pragma unroll
;         for (int mt = 0; mt < 2; ++mt)
; #pragma unroll
;             for (int ks = 0; ks < 2; ++ks) {
;                 const int tq = tt * 32 + mt * 16 + fr; const int pos = nb * 128 + tq; const size_t row = (size_t)b * SEQ + pos;
;                 const bf16_t* qp = Z + row * NZ + O_Q + hq * 64; const int d0 = ks * 32 + q4 * 8;
;                 float qf[8]; unpack8(*(const u32x4*)(qp + d0), qf);
;                 if (ks == 0 && q4 < 2) { float pf[8]; unpack8(*(const u32x4*)(qp + (d0 ^ 8)), pf);
; #pragma unroll
;                     for (int i = 0; i < 8; ++i) { const float c = ct[pos * 8 + i], s = st[pos * 8 + i]; qf[i] = q4 == 0 ? qf[i] * c - pf[i] * s : qf[i] * c + pf[i] * s; } }
; #pragma unroll
;                 for (int i = 0; i < 8; ++i) qf[i] *= 0.18033688011112042f;
;                 Qf[mt][ks] = __builtin_bit_cast(bf16x8, pack8(qf));
;             }
;         float mrow[2][4], lrow[2][4]; f32x4 O[2][4];
; #pragma unroll
;         for (int mt = 0; mt < 2; ++mt) {
; #pragma unroll
;             for (int j = 0; j < 4; ++j) { mrow[mt][j] = sink; lrow[mt][j] = 1.f; }
; #pragma unroll
;             for (int dt = 0; dt < 4; ++dt) O[mt][dt] = (f32x4){0.f, 0.f, 0.f, 0.f};
;         }
;         unsigned short gts[2][4][4];
; #pragma unroll
;         for (int mt = 0; mt < 2; ++mt)
; #pragma unroll
;             for (int j = 0; j < 4; ++j) { const size_t row = (size_t)b * SEQ + nb * 128 + tt * 32 + mt * 16 + q4 * 4 + j;
; #pragma unroll
;                 for (int dt = 0; dt < 4; ++dt) gts[mt][j][dt] = Z[row * NZ + O_GA + hq * 64 + dt * 16 + fr]; }
.LBB0_307:
	s_lshr_b32 s8, s65, 2
	v_mov_b32_e32 v244, s8
	v_lshl_add_u32 v244, v244, 7, v236
	v_add_u32_e32 v245, 0xe000, v244
	v_add_u32_e32 v246, 0x1c000, v244
	v_add_u32_e32 v247, 0x2a000, v244
	global_load_dwordx4 v[180:183], v244, s[98:99]
	global_load_dwordx4 v[184:187], v245, s[98:99]
	global_load_dwordx4 v[188:191], v246, s[98:99]
	global_load_dwordx4 v[192:195], v247, s[98:99]
	s_add_i32 s42, s8, s59
	s_lshl_b64 s[8:9], s[42:43], 2
	s_add_u32 s8, s92, s8
	s_addc_u32 s9, s93, s9
	global_load_dword v28, v67, s[8:9]
	s_lshl_b32 s8, s42, 7
	s_mov_b32 s9, s43
	v_lshl_add_u64 v[2:3], v[94:95], 0, s[8:9]
	v_lshlrev_b32_e32 v66, 1, v90
	v_lshl_add_u64 v[0:1], v[2:3], 0, v[66:67]
	global_load_dwordx4 v[4:7], v[0:1], off
	s_waitcnt vmcnt(0)
	ds_write_b128 v238, v[180:183]
	ds_write_b128 v238, v[184:187] offset:1152
	ds_write_b128 v238, v[188:191] offset:2304
	ds_write_b128 v238, v[192:195] offset:3456
	v_lshlrev_b32_e32 v12, 16, v4
	v_and_b32_e32 v13, 0xffff0000, v4
	v_lshlrev_b32_e32 v14, 16, v5
	v_and_b32_e32 v15, 0xffff0000, v5
	v_lshlrev_b32_e32 v16, 16, v6
	v_and_b32_e32 v17, 0xffff0000, v6
	v_lshlrev_b32_e32 v18, 16, v7
	v_and_b32_e32 v19, 0xffff0000, v7
	v_lshlrev_b32_e32 v4, 1, v64
	s_and_saveexec_b64 s[8:9], s[4:5]
	s_cbranch_execz .LBB0_309
	v_mov_b32_e32 v5, v67
	v_lshl_add_u64 v[2:3], v[2:3], 0, v[4:5]
	global_load_dwordx4 v[6:9], v[2:3], off
	global_load_dwordx4 v[20:23], v[98:99], off
	global_load_dwordx4 v[24:27], v[98:99], off offset:16
	global_load_dwordx4 v[30:33], v[96:97], off
	global_load_dwordx4 v[34:37], v[96:97], off offset:16
	s_waitcnt vmcnt(4)
	v_lshlrev_b32_e32 v2, 16, v6
	v_and_b32_e32 v3, 0xffff0000, v6
	v_lshlrev_b32_e32 v6, 16, v7
	v_and_b32_e32 v7, 0xffff0000, v7
	v_lshlrev_b32_e32 v10, 16, v8
	v_and_b32_e32 v11, 0xffff0000, v8
	v_lshlrev_b32_e32 v8, 16, v9
	v_and_b32_e32 v9, 0xffff0000, v9
	s_waitcnt vmcnt(3)
	v_pk_mul_f32 v[2:3], v[20:21], v[2:3]
	v_pk_mul_f32 v[6:7], v[22:23], v[6:7]
	s_waitcnt vmcnt(2)
	v_pk_mul_f32 v[10:11], v[24:25], v[10:11]
	v_pk_mul_f32 v[8:9], v[26:27], v[8:9]
	v_cndmask_b32_e64 v3, v3, -v3, s[30:31]
	v_cndmask_b32_e64 v2, v2, -v2, s[30:31]
	v_cndmask_b32_e64 v7, v7, -v7, s[30:31]
	v_cndmask_b32_e64 v6, v6, -v6, s[30:31]
	v_cndmask_b32_e64 v11, v11, -v11, s[30:31]
	v_cndmask_b32_e64 v10, v10, -v10, s[30:31]
	v_cndmask_b32_e64 v9, v9, -v9, s[30:31]
	v_cndmask_b32_e64 v8, v8, -v8, s[30:31]
	s_waitcnt vmcnt(1)
	v_pk_fma_f32 v[12:13], v[30:31], v[12:13], v[2:3]
	v_pk_fma_f32 v[14:15], v[32:33], v[14:15], v[6:7]
	s_waitcnt vmcnt(0)
	v_pk_fma_f32 v[16:17], v[34:35], v[16:17], v[10:11]
	v_pk_fma_f32 v[18:19], v[36:37], v[18:19], v[8:9]

; __device__ __forceinline__ void unpack8(u32x4 u, float* f) { f[0] = bflo(u.x); f[1] = bfhi(u.x); f[2] = bflo(u.y); f[3] = bfhi(u.y); f[4] = bflo(u.z); f[5] = bfhi(u.z); f[6] = bflo(u.w); f[7] = bfhi(u.w); }
; __device__ __forceinline__ u32x4 pack8(const float* f) { u32x4 o; o.x = pk2(f[0], f[1]); o.y = pk2(f[2], f[3]); o.z = pk2(f[4], f[5]); o.w = pk2(f[6], f[7]); return o; }
; __device__ __forceinline__ void attn_prompt_item(const Args& A, LAS unsigned char* lds, int tid, int lane, int wave, int b, int nb, int kvh) {
;     ...
;                 const int tq = tt * 32 + mt * 16 + fr; const int pos = nb * 128 + tq; const size_t row = (size_t)b * SEQ + pos;
;                 const bf16_t* qp = Z + row * NZ + O_Q + hq * 64; const int d0 = ks * 32 + q4 * 8;
;                 float qf[8]; unpack8(*(const u32x4*)(qp + d0), qf);
;                 if (ks == 0 && q4 < 2) { float pf[8]; unpack8(*(const u32x4*)(qp + (d0 ^ 8)), pf);
; #pragma unroll
;                     for (int i = 0; i < 8; ++i) { const float c = ct[pos * 8 + i], s = st[pos * 8 + i]; qf[i] = q4 == 0 ? qf[i] * c - pf[i] * s : qf[i] * c + pf[i] * s; } }
; #pragma unroll
;                 for (int i = 0; i < 8; ++i) qf[i] *= 0.18033688011112042f;
;                 Qf[mt][ks] = __builtin_bit_cast(bf16x8, pack8(qf));
;             }
;         float mrow[2][4], lrow[2][4]; f32x4 O[2][4];
; #pragma unroll
;         for (int mt = 0; mt < 2; ++mt) {
; #pragma unroll
;             for (int j = 0; j < 4; ++j) { mrow[mt][j] = sink; lrow[mt][j] = 1.f; }
; #pragma unroll
;             for (int dt = 0; dt < 4; ++dt) O[mt][dt] = (f32x4){0.f, 0.f, 0.f, 0.f};
;         }
;         unsigned short gts[2][4][4];
; #pragma unroll
;         for (int mt = 0; mt < 2; ++mt)
; #pragma unroll
;             for (int j = 0; j < 4; ++j) { const size_t row = (size_t)b * SEQ + nb * 128 + tt * 32 + mt * 16 + q4 * 4 + j;
; #pragma unroll
;                 for (int dt = 0; dt < 4; ++dt) gts[mt][j][dt] = Z[row * NZ + O_GA + hq * 64 + dt * 16 + fr]; }
.LBB0_313:
	s_or_b64 exec, exec, s[8:9]
	v_mov_b32_e32 v1, v20
	v_pk_mul_f32 v[20:21], v[24:25], s[48:49] op_sel_hi:[1,0]
	v_lshl_add_u64 v[24:25], v[112:113], 0, s[42:43]
	global_load_dwordx4 v[44:47], v[22:23], off offset:64
	v_lshl_add_u64 v[26:27], v[114:115], 0, s[42:43]
	v_lshl_add_u64 v[30:31], v[116:117], 0, s[42:43]
	v_lshl_add_u64 v[36:37], v[118:119], 0, s[42:43]
	v_lshl_add_u64 v[38:39], v[120:121], 0, s[42:43]
	v_lshl_add_u64 v[40:41], v[122:123], 0, s[42:43]
	v_lshl_add_u64 v[42:43], v[124:125], 0, s[42:43]
	v_lshl_add_u64 v[48:49], v[126:127], 0, s[42:43]
	ds_read_u16 v213, v239 offset:0
	ds_read_u16 v111, v239 offset:32
	ds_read_u16 v212, v239 offset:64
	ds_read_u16 v89, v239 offset:96
	ds_read_u16 v211, v239 offset:144
	ds_read_u16 v210, v239 offset:176
	ds_read_u16 v203, v239 offset:208
	ds_read_u16 v202, v239 offset:240
	ds_read_u16 v201, v239 offset:288
	ds_read_u16 v200, v239 offset:320
	ds_read_u16 v199, v239 offset:352
	ds_read_u16 v198, v239 offset:384
	ds_read_u16 v197, v239 offset:432
	ds_read_u16 v196, v239 offset:464
	ds_read_u16 v195, v239 offset:496
	ds_read_u16 v194, v239 offset:528
	ds_read_u16 v193, v239 offset:2304
	ds_read_u16 v192, v239 offset:2336
	ds_read_u16 v191, v239 offset:2368
	ds_read_u16 v190, v239 offset:2400
	ds_read_u16 v189, v239 offset:2448
	ds_read_u16 v188, v239 offset:2480
	ds_read_u16 v187, v239 offset:2512
	ds_read_u16 v186, v239 offset:2544
	ds_read_u16 v185, v239 offset:2592
	ds_read_u16 v184, v239 offset:2624
	ds_read_u16 v183, v239 offset:2656
	ds_read_u16 v182, v239 offset:2688
	ds_read_u16 v181, v239 offset:2736
	ds_read_u16 v180, v239 offset:2768
	ds_read_u16 v179, v239 offset:2800
	ds_read_u16 v66, v239 offset:2832
	v_pk_mul_f32 v[4:5], v[12:13], s[48:49] op_sel_hi:[1,0]
	v_pk_mul_f32 v[12:13], v[14:15], s[48:49] op_sel_hi:[1,0]
	v_pk_mul_f32 v[14:15], v[16:17], s[48:49] op_sel_hi:[1,0]
	v_pk_mul_f32 v[16:17], v[18:19], s[48:49] op_sel_hi:[1,0]
	s_waitcnt vmcnt(1)
	v_lshlrev_b32_e32 v18, 16, v8
	v_and_b32_e32 v19, 0xffff0000, v8
	v_pk_mul_f32 v[0:1], v[0:1], s[48:49] op_sel_hi:[1,0]
	v_pk_mul_f32 v[6:7], v[6:7], s[48:49] op_sel_hi:[1,0]
	v_pk_mul_f32 v[2:3], v[2:3], s[48:49] op_sel_hi:[1,0]
	v_cvt_pk_bf16_f32 v32, v4, v5
	v_pk_mul_f32 v[4:5], v[18:19], s[48:49] op_sel_hi:[1,0]
	v_cvt_pk_bf16_f32 v36, v0, v1
	v_lshlrev_b32_e32 v8, 16, v9
	v_and_b32_e32 v9, 0xffff0000, v9
	v_lshlrev_b32_e32 v22, 16, v10
	v_and_b32_e32 v23, 0xffff0000, v10
	v_lshlrev_b32_e32 v10, 16, v11
	v_and_b32_e32 v11, 0xffff0000, v11
	v_cvt_pk_bf16_f32 v37, v6, v7
	v_cvt_pk_bf16_f32 v39, v2, v3
	v_cvt_pk_bf16_f32 v40, v4, v5
	v_cvt_pk_bf16_f32 v33, v12, v13
	v_pk_mul_f32 v[8:9], v[8:9], s[48:49] op_sel_hi:[1,0]
	v_pk_mul_f32 v[12:13], v[22:23], s[48:49] op_sel_hi:[1,0]
	v_pk_mul_f32 v[10:11], v[10:11], s[48:49] op_sel_hi:[1,0]
	v_mul_f32_e32 v172, 0x3fb8aa3b, v28
	v_mov_b32_e32 v170, 1.0
	v_cvt_pk_bf16_f32 v34, v14, v15
	v_cvt_pk_bf16_f32 v35, v16, v17
	v_cvt_pk_bf16_f32 v38, v20, v21
	v_cvt_pk_bf16_f32 v41, v8, v9
	v_cvt_pk_bf16_f32 v42, v12, v13
	v_cvt_pk_bf16_f32 v43, v10, v11
	v_mov_b32_e32 v214, v178
	v_mov_b32_e32 v217, v177
	v_mov_b32_e32 v215, v176
	v_mov_b32_e32 v216, v147
	v_mov_b32_e32 v173, v172
	v_mov_b32_e32 v174, v172
	v_mov_b32_e32 v175, v172
	v_mov_b32_e32 v228, v172
	v_mov_b32_e32 v226, v172
	v_mov_b32_e32 v222, v172
	v_mov_b32_e32 v220, v172
	s_mov_b32 s78, s64
	v_mov_b32_e32 v171, v170
	v_mov_b32_e32 v168, v170
	v_mov_b32_e32 v169, v170
	v_mov_b32_e32 v166, v170
	v_mov_b32_e32 v167, v170
	v_mov_b32_e32 v164, v170
	v_mov_b32_e32 v165, v170
	s_waitcnt vmcnt(0)
	v_lshlrev_b32_e32 v0, 16, v44
	v_and_b32_e32 v1, 0xffff0000, v44
	v_lshlrev_b32_e32 v2, 16, v45
	v_and_b32_e32 v3, 0xffff0000, v45
	v_lshlrev_b32_e32 v4, 16, v46
	v_and_b32_e32 v5, 0xffff0000, v46
	v_pk_mul_f32 v[0:1], v[0:1], s[48:49] op_sel_hi:[1,0]
	v_lshlrev_b32_e32 v6, 16, v47
	v_and_b32_e32 v7, 0xffff0000, v47
	v_pk_mul_f32 v[2:3], v[2:3], s[48:49] op_sel_hi:[1,0]
	v_pk_mul_f32 v[4:5], v[4:5], s[48:49] op_sel_hi:[1,0]
	v_pk_mul_f32 v[6:7], v[6:7], s[48:49] op_sel_hi:[1,0]
	v_cvt_pk_bf16_f32 v44, v0, v1
	v_mov_b32_e32 v0, 0
	v_cvt_pk_bf16_f32 v45, v2, v3
	v_cvt_pk_bf16_f32 v46, v4, v5
	v_cvt_pk_bf16_f32 v47, v6, v7
	v_mov_b32_e32 v1, v0
	v_mov_b32_e32 v2, v0
	v_mov_b32_e32 v3, v0
	v_mov_b32_e32 v4, v0
	v_mov_b32_e32 v5, v0
	v_mov_b32_e32 v6, v0
	v_mov_b32_e32 v7, v0
	v_mov_b32_e32 v8, v0
	v_mov_b32_e32 v9, v0
	v_mov_b32_e32 v10, v0
	v_mov_b32_e32 v11, v0
	v_mov_b32_e32 v12, v0
	v_mov_b32_e32 v13, v0
	v_mov_b32_e32 v14, v0
	v_mov_b32_e32 v15, v0
	v_mov_b32_e32 v16, v0
	v_mov_b32_e32 v17, v0
	v_mov_b32_e32 v18, v0
	v_mov_b32_e32 v19, v0
	v_mov_b32_e32 v20, v0
	v_mov_b32_e32 v21, v0
	v_mov_b32_e32 v22, v0
	v_mov_b32_e32 v23, v0
	v_mov_b32_e32 v24, v0
	v_mov_b32_e32 v25, v0
	v_mov_b32_e32 v26, v0
	v_mov_b32_e32 v27, v0
	v_mov_b32_e32 v28, v0
	v_mov_b32_e32 v29, v0
	v_mov_b32_e32 v30, v0
	v_mov_b32_e32 v31, v0
; #define LAS __attribute__((address_space(3)))
; __device__ __forceinline__ float red16_sum(float x) { x = red8_sum(x); x += dppf<0x140>(x); return x; }
; __device__ __forceinline__ float red16_max(float x) { x = fmaxf(x, dppf<0xB1>(x)); x = fmaxf(x, dppf<0x4E>(x)); x = fmaxf(x, dppf<0x141>(x)); x = fmaxf(x, dppf<0x140>(x)); return x; }
; __device__ __forceinline__ void attn_prompt_item(const Args& A, LAS unsigned char* lds, int tid, int lane, int wave, int b, int nb, int kvh) {
;     ...
;             for (int mt = 0; mt < 2; ++mt) {
;                 f32x4 S[4];
; #pragma unroll
;                 for (int nt = 0; nt < 4; ++nt) {
;                     f32x4 acc = {0.f, 0.f, 0.f, 0.f};
; #pragma unroll
;                     for (int ks = 0; ks < 2; ++ks) { const bf16x8 Bk = *(const LAS bf16x8*)(lds + AT_K + (kc * 64 + nt * 16 + fr) * 144 + (ks * 32 + q4 * 8) * 2);
;                         acc = __builtin_amdgcn_mfma_f32_16x16x32_bf16(Qf[mt][ks], Bk, acc, 0, 0, 0); }
;                     S[nt] = acc;
;                 }
;                 float alpha[4];
; #pragma unroll
;                 for (int j = 0; j < 4; ++j) {
;                     const int dq = kc * 64 + fr - (tt * 32 + mt * 16 + q4 * 4 + j) - 1;
;                     float mx = -1e30f;
; #pragma unroll
;                     for (int nt = 0; nt < 4; ++nt) { const bool ok = (unsigned)(dq + nt * 16) < 128u;
;                         const float s = ok ? S[nt][j] : -1e30f; S[nt][j] = s; mx = fmaxf(mx, s); }
;                     mx = red16_max(mx);
;                     const float mn = fmaxf(mrow[mt][j], mx); alpha[j] = __builtin_amdgcn_exp2f(mrow[mt][j] - mn); mrow[mt][j] = mn;
;                     float rs = 0.f;
; #pragma unroll
;                     for (int nt = 0; nt < 4; ++nt) { const float p = __builtin_amdgcn_exp2f(S[nt][j] - mn); S[nt][j] = p; rs += p; }
;                     rs = red16_sum(rs); lrow[mt][j] = lrow[mt][j] * alpha[j] + rs;
;                 }
.LBB0_314:
	ds_read_b128 v[48:51], v214
	ds_read_b128 v[52:55], v214 offset:64
	v_subrev_u32_e32 v218, 19, v217
	v_cmp_lt_u32_e32 vcc, s57, v218
	v_subrev_u32_e32 v218, 35, v217
	s_waitcnt lgkmcnt(1)
	v_mfma_f32_16x16x32_bf16 v[48:51], v[32:35], v[48:51], 0
	v_cmp_lt_u32_e64 s[8:9], s57, v218
	v_subrev_u32_e32 v218, 51, v217
	v_cmp_lt_u32_e64 s[12:13], s57, v218
	s_waitcnt lgkmcnt(0)
	v_mfma_f32_16x16x32_bf16 v[56:59], v[40:43], v[52:55], v[48:51]
	ds_read_b128 v[52:55], v214 offset:2368
	v_add_u32_e32 v218, 0xffffffbd, v217
	v_cmp_lt_u32_e64 s[10:11], s57, v218
	ds_read_b128 v[48:51], v214 offset:2304
	s_waitcnt lgkmcnt(0)
	v_mfma_f32_16x16x32_bf16 v[48:51], v[32:35], v[48:51], 0
	s_nop 1
	v_cndmask_b32_e32 v56, v143, v56, vcc
	v_mov_b32_e32 v234, 0
	v_mov_b32_e32 v235, 0
	v_mfma_f32_16x16x32_bf16 v[60:63], v[40:43], v[52:55], v[48:51]
	ds_read_b128 v[52:55], v214 offset:4672
	v_mov_b32_e32 v227, 0
	s_add_i32 s78, s78, 1
	ds_read_b128 v[48:51], v214 offset:4608
	s_waitcnt lgkmcnt(0)
	v_mfma_f32_16x16x32_bf16 v[48:51], v[32:35], v[48:51], 0
	ds_read_b128 v[230:233], v214 offset:6976
	s_nop 0
	v_cndmask_b32_e64 v219, v143, v60, s[8:9]
	v_max3_f32 v60, v56, s58, v219
	v_mfma_f32_16x16x32_bf16 v[48:51], v[40:43], v[52:55], v[48:51]
	ds_read_b128 v[52:55], v214 offset:6912
	s_cmp_ge_u32 s78, s53
	s_waitcnt lgkmcnt(0)
	v_mfma_f32_16x16x32_bf16 v[52:55], v[32:35], v[52:55], 0
	s_nop 3
	v_cndmask_b32_e64 v48, v143, v48, s[12:13]
	v_mfma_f32_16x16x32_bf16 v[52:55], v[40:43], v[230:233], v[52:55]
	v_mov_b32_e32 v230, 0
	v_mov_b32_e32 v231, 0
	s_nop 5
	v_cndmask_b32_e64 v221, v143, v52, s[10:11]
	v_max3_f32 v52, v60, v48, v221
	v_mov_b32_e32 v60, 0
	s_nop 1
	v_mov_b32_dpp v60, v52 quad_perm:[1,0,3,2] row_mask:0xf bank_mask:0xf
	v_max_f32_e32 v60, v60, v60
	v_max_f32_e32 v52, v52, v60
	v_mov_b32_e32 v60, 0
	s_nop 1
	v_mov_b32_dpp v60, v52 quad_perm:[2,3,0,1] row_mask:0xf bank_mask:0xf
	v_max_f32_e32 v60, v60, v60
	v_max_f32_e32 v52, v52, v60
	v_mov_b32_e32 v60, 0
	s_nop 1
	v_mov_b32_dpp v60, v52 row_half_mirror row_mask:0xf bank_mask:0xf
	v_max_f32_e32 v60, v60, v60
	v_max_f32_e32 v52, v52, v60
	v_mov_b32_e32 v60, 0
	s_nop 1
	v_mov_b32_dpp v60, v52 row_mirror row_mask:0xf bank_mask:0xf
	v_max3_f32 v218, v172, v52, v60
	v_sub_f32_e32 v52, v172, v218
	v_exp_f32_e32 v172, v52
	v_sub_f32_e32 v52, v56, v218
	v_exp_f32_e32 v60, v52
	v_sub_f32_e32 v52, v219, v218
	v_subrev_u32_e32 v219, 18, v217
	v_cmp_lt_u32_e64 s[10:11], s57, v219
	v_subrev_u32_e32 v219, 34, v217
	v_cmp_lt_u32_e64 s[14:15], s57, v219
	v_subrev_u32_e32 v219, 50, v217
	v_sub_f32_e32 v48, v48, v218
	v_cmp_lt_u32_e64 s[18:19], s57, v219
	v_add_u32_e32 v219, 0xffffffbe, v217
	v_exp_f32_e32 v56, v52
	v_exp_f32_e32 v52, v48
	v_sub_f32_e32 v48, v221, v218
	v_cndmask_b32_e64 v57, v143, v57, s[10:11]
	v_cndmask_b32_e64 v221, v143, v61, s[14:15]
	v_cmp_lt_u32_e64 s[16:17], s57, v219
	v_max3_f32 v61, v57, s58, v221
	v_cndmask_b32_e64 v49, v143, v49, s[18:19]
	v_cndmask_b32_e64 v223, v143, v53, s[16:17]
	v_max3_f32 v53, v61, v49, v223
	v_mov_b32_e32 v61, 0
	v_exp_f32_e32 v48, v48
	s_nop 0
	v_mov_b32_dpp v61, v53 quad_perm:[1,0,3,2] row_mask:0xf bank_mask:0xf
	v_max_f32_e32 v61, v61, v61
	v_max_f32_e32 v53, v53, v61
	v_mov_b32_e32 v61, 0
	s_nop 1
	v_mov_b32_dpp v61, v53 quad_perm:[2,3,0,1] row_mask:0xf bank_mask:0xf
	v_max_f32_e32 v61, v61, v61
	v_max_f32_e32 v53, v53, v61
	v_mov_b32_e32 v61, 0
	s_nop 1
	v_mov_b32_dpp v61, v53 row_half_mirror row_mask:0xf bank_mask:0xf
	v_max_f32_e32 v61, v61, v61
	v_max_f32_e32 v53, v53, v61
	v_mov_b32_e32 v61, 0
	s_nop 1
	v_mov_b32_dpp v61, v53 row_mirror row_mask:0xf bank_mask:0xf
	v_max3_f32 v219, v173, v53, v61
	v_sub_f32_e32 v53, v173, v219
	v_exp_f32_e32 v173, v53
	v_sub_f32_e32 v53, v57, v219
	v_exp_f32_e32 v61, v53
	v_sub_f32_e32 v53, v221, v219
	v_exp_f32_e32 v57, v53
	v_sub_f32_e32 v49, v49, v219
	v_exp_f32_e32 v53, v49
	v_sub_f32_e32 v49, v223, v219
	v_exp_f32_e32 v49, v49
	v_pk_add_f32 v[224:225], v[60:61], 0 op_sel_hi:[1,0]
	v_subrev_u32_e32 v221, 17, v217
	v_pk_add_f32 v[224:225], v[56:57], v[224:225]
	v_cmp_lt_u32_e64 s[16:17], s57, v221
	v_pk_add_f32 v[224:225], v[52:53], v[224:225]
	v_subrev_u32_e32 v221, 33, v217
	v_pk_add_f32 v[224:225], v[48:49], v[224:225]
	v_subrev_u32_e32 v223, 49, v217
	v_cmp_lt_u32_e64 s[20:21], s57, v221
	v_mov_b32_dpp v230, v224 quad_perm:[1,0,3,2] row_mask:0xf bank_mask:0xf
	v_mov_b32_dpp v231, v225 quad_perm:[1,0,3,2] row_mask:0xf bank_mask:0xf
	v_pk_add_f32 v[224:225], v[224:225], v[230:231]
	v_mov_b32_e32 v230, 0
	v_mov_b32_e32 v231, 0
	v_cmp_lt_u32_e64 s[22:23], s57, v223
	v_mov_b32_dpp v230, v224 quad_perm:[2,3,0,1] row_mask:0xf bank_mask:0xf
	v_mov_b32_dpp v231, v225 quad_perm:[2,3,0,1] row_mask:0xf bank_mask:0xf
	v_pk_add_f32 v[224:225], v[224:225], v[230:231]
	v_mov_b32_e32 v230, 0
	v_mov_b32_e32 v231, 0
	v_add_u32_e32 v223, 0xffffffbf, v217
	v_mov_b32_dpp v230, v224 row_half_mirror row_mask:0xf bank_mask:0xf
	v_mov_b32_dpp v231, v225 row_half_mirror row_mask:0xf bank_mask:0xf
	v_pk_add_f32 v[224:225], v[224:225], v[230:231]
	v_mov_b32_e32 v230, 0
	v_mov_b32_e32 v231, 0
	v_cndmask_b32_e64 v58, v143, v58, s[16:17]
	v_mov_b32_dpp v230, v224 row_mirror row_mask:0xf bank_mask:0xf
	v_mov_b32_dpp v231, v225 row_mirror row_mask:0xf bank_mask:0xf
	v_pk_add_f32 v[224:225], v[224:225], v[230:231]
	v_cndmask_b32_e64 v221, v143, v62, s[20:21]
	v_cmp_lt_u32_e64 s[24:25], s57, v223
	v_pk_fma_f32 v[170:171], v[170:171], v[172:173], v[224:225]
	v_max3_f32 v62, v58, s58, v221
	v_cndmask_b32_e64 v50, v143, v50, s[22:23]
	v_cndmask_b32_e64 v224, v143, v54, s[24:25]
	v_max3_f32 v54, v62, v50, v224
	v_mov_b32_e32 v62, 0
; #define LAS __attribute__((address_space(3)))
; __device__ __forceinline__ unsigned f2bf(float f) { return pk2(f, 0.f) & 0xffffu; }
; __device__ __forceinline__ float red16_sum(float x) { x = red8_sum(x); x += dppf<0x140>(x); return x; }
; #define LDS_WAIT() asm volatile("s_waitcnt lgkmcnt(0)" ::: "memory")
; __device__ __forceinline__ void attn_prompt_item(const Args& A, LAS unsigned char* lds, int tid, int lane, int wave, int b, int nb, int kvh) {
;     ...
;                 float alpha[4];
; #pragma unroll
;                 for (int j = 0; j < 4; ++j) {
;                     const int dq = kc * 64 + fr - (tt * 32 + mt * 16 + q4 * 4 + j) - 1;
;                     float mx = -1e30f;
; #pragma unroll
;                     for (int nt = 0; nt < 4; ++nt) { const bool ok = (unsigned)(dq + nt * 16) < 128u;
;                         const float s = ok ? S[nt][j] : -1e30f; S[nt][j] = s; mx = fmaxf(mx, s); }
;                     mx = red16_max(mx);
;                     const float mn = fmaxf(mrow[mt][j], mx); alpha[j] = __builtin_amdgcn_exp2f(mrow[mt][j] - mn); mrow[mt][j] = mn;
;                     float rs = 0.f;
; #pragma unroll
;                     for (int nt = 0; nt < 4; ++nt) { const float p = __builtin_amdgcn_exp2f(S[nt][j] - mn); S[nt][j] = p; rs += p; }
;                     rs = red16_sum(rs); lrow[mt][j] = lrow[mt][j] * alpha[j] + rs;
;                 }
; #pragma unroll
;                 for (int dt = 0; dt < 4; ++dt)
; #pragma unroll
;                     for (int j = 0; j < 4; ++j) O[mt][dt][j] *= alpha[j];
; #pragma unroll
;                 for (int nt = 0; nt < 4; ++nt)
; #pragma unroll
;                     for (int j = 0; j < 4; ++j) *(LAS unsigned short*)(Pw + (q4 * 4 + j) * 144 + (nt * 16 + fr) * 2) = (unsigned short)f2bf(S[nt][j]);
;                 LDS_WAIT();
;                 bf16x8 Pa[2];
; #pragma unroll
;                 for (int ks = 0; ks < 2; ++ks) Pa[ks] = *(const LAS bf16x8*)(Pw + fr * 144 + (ks * 32 + q4 * 8) * 2);
; #pragma unroll
;                 for (int dt = 0; dt < 4; ++dt)
; #pragma unroll
;                     for (int ks = 0; ks < 2; ++ks) { const bf16x8 Bv = *(const LAS bf16x8*)(lds + AT_V + (dt * 16 + fr) * 528 + (kc * 64 + ks * 32 + q4 * 8) * 2);
;                         O[mt][dt] = __builtin_amdgcn_mfma_f32_16x16x32_bf16(Pa[ks], Bv, O[mt][dt], 0, 0, 0); }
	v_subrev_u32_e32 v230, 64, v217
	v_cmp_lt_u32_e64 s[34:35], s57, v230
	v_mov_b32_dpp v62, v54 quad_perm:[1,0,3,2] row_mask:0xf bank_mask:0xf
	v_max_f32_e32 v62, v62, v62
	v_max_f32_e32 v54, v54, v62
	v_mov_b32_e32 v62, 0
	v_cvt_pk_bf16_f32 v60, v60, s0
	v_cvt_pk_bf16_f32 v56, v56, s0
	v_mov_b32_dpp v62, v54 quad_perm:[2,3,0,1] row_mask:0xf bank_mask:0xf
	v_max_f32_e32 v62, v62, v62
	v_max_f32_e32 v54, v54, v62
	v_mov_b32_e32 v62, 0
	v_cvt_pk_bf16_f32 v52, v52, s0
	v_cvt_pk_bf16_f32 v48, v48, s0
	v_mov_b32_dpp v62, v54 row_half_mirror row_mask:0xf bank_mask:0xf
	v_max_f32_e32 v62, v62, v62
	v_max_f32_e32 v54, v54, v62
	v_mov_b32_e32 v62, 0
	ds_write_b16 v85, v60
	v_cvt_pk_bf16_f32 v60, v61, s0
	v_mov_b32_dpp v62, v54 row_mirror row_mask:0xf bank_mask:0xf
	v_max3_f32 v223, v174, v54, v62
	v_sub_f32_e32 v54, v174, v223
	v_exp_f32_e32 v174, v54
	v_sub_f32_e32 v54, v58, v223
	v_exp_f32_e32 v62, v54
	v_sub_f32_e32 v54, v221, v223
	v_add_u32_e32 v221, -16, v217
	v_sub_f32_e32 v50, v50, v223
	v_cmp_lt_u32_e64 s[24:25], s57, v221
	v_subrev_u32_e32 v221, 32, v217
	v_exp_f32_e32 v58, v54
	v_exp_f32_e32 v54, v50
	v_sub_f32_e32 v50, v224, v223
	v_cmp_lt_u32_e64 s[26:27], s57, v221
	v_subrev_u32_e32 v224, 48, v217
	v_cndmask_b32_e64 v59, v143, v59, s[24:25]
	v_cndmask_b32_e64 v221, v143, v63, s[26:27]
	v_cmp_lt_u32_e64 s[28:29], s57, v224
	v_max3_f32 v63, v59, s58, v221
	v_cndmask_b32_e64 v224, v143, v55, s[34:35]
	v_cndmask_b32_e64 v51, v143, v51, s[28:29]
	v_max3_f32 v55, v63, v51, v224
	v_mov_b32_e32 v63, 0
	v_exp_f32_e32 v50, v50
	ds_write_b16 v85, v56 offset:32
	v_mov_b32_dpp v63, v55 quad_perm:[1,0,3,2] row_mask:0xf bank_mask:0xf
	v_max_f32_e32 v63, v63, v63
	v_max_f32_e32 v55, v55, v63
	v_mov_b32_e32 v63, 0
	v_cvt_pk_bf16_f32 v56, v57, s0
	ds_write_b16 v85, v52 offset:64
	v_mov_b32_dpp v63, v55 quad_perm:[2,3,0,1] row_mask:0xf bank_mask:0xf
	v_max_f32_e32 v63, v63, v63
	v_max_f32_e32 v55, v55, v63
	v_mov_b32_e32 v63, 0
	v_cvt_pk_bf16_f32 v52, v53, s0
	ds_write_b16 v85, v48 offset:96
	v_mov_b32_dpp v63, v55 row_half_mirror row_mask:0xf bank_mask:0xf
	v_max_f32_e32 v63, v63, v63
	v_max_f32_e32 v55, v55, v63
	v_mov_b32_e32 v63, 0
	v_cvt_pk_bf16_f32 v48, v49, s0
	ds_write_b16 v85, v60 offset:144
	v_mov_b32_dpp v63, v55 row_mirror row_mask:0xf bank_mask:0xf
	v_max3_f32 v225, v175, v55, v63
	v_sub_f32_e32 v55, v175, v225
	v_exp_f32_e32 v175, v55
	v_sub_f32_e32 v55, v59, v225
	v_exp_f32_e32 v63, v55
	v_sub_f32_e32 v55, v221, v225
	v_sub_f32_e32 v51, v51, v225
	v_exp_f32_e32 v59, v55
	v_exp_f32_e32 v55, v51
	v_sub_f32_e32 v51, v224, v225
	v_exp_f32_e32 v51, v51
	v_cvt_pk_bf16_f32 v60, v62, s0
	ds_write_b16 v85, v56 offset:176
	v_cvt_pk_bf16_f32 v56, v58, s0
	ds_write_b16 v85, v52 offset:208
	v_cvt_pk_bf16_f32 v52, v54, s0
	ds_write_b16 v85, v48 offset:240
	v_cvt_pk_bf16_f32 v48, v50, s0
	v_pk_add_f32 v[232:233], v[62:63], 0 op_sel_hi:[1,0]
	ds_write_b16 v85, v60 offset:288
	v_cvt_pk_bf16_f32 v60, v63, s0
	ds_write_b16 v85, v56 offset:320
	v_cvt_pk_bf16_f32 v56, v59, s0
	ds_write_b16 v85, v52 offset:352
	v_cvt_pk_bf16_f32 v52, v55, s0
	ds_write_b16 v85, v48 offset:384
	v_cvt_pk_bf16_f32 v48, v51, s0
	v_pk_add_f32 v[232:233], v[58:59], v[232:233]
	ds_write_b16 v85, v60 offset:432
	ds_write_b16 v85, v56 offset:464
	ds_write_b16 v85, v52 offset:496
	ds_write_b16 v85, v48 offset:528
	v_pk_add_f32 v[232:233], v[54:55], v[232:233]
	s_waitcnt lgkmcnt(0)
	v_pk_mul_f32 v[30:31], v[30:31], v[174:175]
	v_pk_add_f32 v[232:233], v[50:51], v[232:233]
	ds_read_b128 v[48:51], v91
	ds_read_b128 v[52:55], v91 offset:64
	ds_read_b128 v[56:59], v215
	v_pk_mul_f32 v[28:29], v[28:29], v[172:173]
	v_pk_mul_f32 v[26:27], v[26:27], v[174:175]
	v_pk_mul_f32 v[24:25], v[24:25], v[172:173]
	s_waitcnt lgkmcnt(0)
	v_mfma_f32_16x16x32_bf16 v[28:31], v[48:51], v[56:59], v[28:31]
	ds_read_b128 v[56:59], v215 offset:64
	v_pk_mul_f32 v[22:23], v[22:23], v[174:175]
	v_pk_mul_f32 v[20:21], v[20:21], v[172:173]
	s_waitcnt lgkmcnt(0)
	v_mfma_f32_16x16x32_bf16 v[28:31], v[52:55], v[56:59], v[28:31]
	ds_read_b128 v[56:59], v215 offset:8448
	v_pk_mul_f32 v[18:19], v[18:19], v[174:175]
	v_pk_mul_f32 v[16:17], v[16:17], v[172:173]
	s_waitcnt lgkmcnt(0)
	v_mfma_f32_16x16x32_bf16 v[24:27], v[48:51], v[56:59], v[24:27]
	ds_read_b128 v[56:59], v215 offset:8512
	v_mov_b32_dpp v234, v232 quad_perm:[1,0,3,2] row_mask:0xf bank_mask:0xf
	v_mov_b32_dpp v235, v233 quad_perm:[1,0,3,2] row_mask:0xf bank_mask:0xf
	s_waitcnt lgkmcnt(0)
	v_mfma_f32_16x16x32_bf16 v[24:27], v[52:55], v[56:59], v[24:27]
	ds_read_b128 v[56:59], v215 offset:16896
	v_pk_add_f32 v[232:233], v[232:233], v[234:235]
	v_mov_b32_e32 v234, 0
	s_waitcnt lgkmcnt(0)
	v_mfma_f32_16x16x32_bf16 v[20:23], v[48:51], v[56:59], v[20:23]
	ds_read_b128 v[56:59], v215 offset:16960
	v_mov_b32_e32 v235, 0
	v_mov_b32_dpp v234, v232 quad_perm:[2,3,0,1] row_mask:0xf bank_mask:0xf
	s_waitcnt lgkmcnt(0)
	v_mfma_f32_16x16x32_bf16 v[20:23], v[52:55], v[56:59], v[20:23]
	ds_read_b128 v[56:59], v216
	v_mov_b32_dpp v235, v233 quad_perm:[2,3,0,1] row_mask:0xf bank_mask:0xf
	v_pk_add_f32 v[232:233], v[232:233], v[234:235]
	s_waitcnt lgkmcnt(0)
	v_mfma_f32_16x16x32_bf16 v[16:19], v[48:51], v[56:59], v[16:19]
	ds_read_b128 v[48:51], v216 offset:64
	s_waitcnt lgkmcnt(0)
	ds_read_b128 v[56:59], v214 offset:2368
	s_waitcnt lgkmcnt(1)
	v_mfma_f32_16x16x32_bf16 v[16:19], v[52:55], v[48:51], v[16:19]
	ds_read_b128 v[48:51], v214
	ds_read_b128 v[52:55], v214 offset:64
	ds_read_b128 v[60:63], v214 offset:4672
	s_waitcnt lgkmcnt(2)
	v_mfma_f32_16x16x32_bf16 v[48:51], v[36:39], v[48:51], 0
	v_mov_b32_e32 v234, 0
	v_mov_b32_e32 v235, 0
	s_waitcnt lgkmcnt(1)
; #define LAS __attribute__((address_space(3)))
; __device__ __forceinline__ float red16_sum(float x) { x = red8_sum(x); x += dppf<0x140>(x); return x; }
; __device__ __forceinline__ float red16_max(float x) { x = fmaxf(x, dppf<0xB1>(x)); x = fmaxf(x, dppf<0x4E>(x)); x = fmaxf(x, dppf<0x141>(x)); x = fmaxf(x, dppf<0x140>(x)); return x; }
; __device__ __forceinline__ void attn_prompt_item(const Args& A, LAS unsigned char* lds, int tid, int lane, int wave, int b, int nb, int kvh) {
;     ...
;             for (int mt = 0; mt < 2; ++mt) {
;                 f32x4 S[4];
; #pragma unroll
;                 for (int nt = 0; nt < 4; ++nt) {
;                     f32x4 acc = {0.f, 0.f, 0.f, 0.f};
; #pragma unroll
;                     for (int ks = 0; ks < 2; ++ks) { const bf16x8 Bk = *(const LAS bf16x8*)(lds + AT_K + (kc * 64 + nt * 16 + fr) * 144 + (ks * 32 + q4 * 8) * 2);
;                         acc = __builtin_amdgcn_mfma_f32_16x16x32_bf16(Qf[mt][ks], Bk, acc, 0, 0, 0); }
;                     S[nt] = acc;
;                 }
;                 float alpha[4];
; #pragma unroll
;                 for (int j = 0; j < 4; ++j) {
;                     const int dq = kc * 64 + fr - (tt * 32 + mt * 16 + q4 * 4 + j) - 1;
;                     float mx = -1e30f;
; #pragma unroll
;                     for (int nt = 0; nt < 4; ++nt) { const bool ok = (unsigned)(dq + nt * 16) < 128u;
;                         const float s = ok ? S[nt][j] : -1e30f; S[nt][j] = s; mx = fmaxf(mx, s); }
;                     mx = red16_max(mx);
;                     const float mn = fmaxf(mrow[mt][j], mx); alpha[j] = __builtin_amdgcn_exp2f(mrow[mt][j] - mn); mrow[mt][j] = mn;
;                     float rs = 0.f;
; #pragma unroll
;                     for (int nt = 0; nt < 4; ++nt) { const float p = __builtin_amdgcn_exp2f(S[nt][j] - mn); S[nt][j] = p; rs += p; }
;                     rs = red16_sum(rs); lrow[mt][j] = lrow[mt][j] * alpha[j] + rs;
;                 }
	v_mfma_f32_16x16x32_bf16 v[48:51], v[44:47], v[52:55], v[48:51]
	ds_read_b128 v[52:55], v214 offset:2304
	v_mov_b32_dpp v234, v232 row_half_mirror row_mask:0xf bank_mask:0xf
	v_mov_b32_dpp v235, v233 row_half_mirror row_mask:0xf bank_mask:0xf
	s_waitcnt lgkmcnt(0)
	v_mfma_f32_16x16x32_bf16 v[52:55], v[36:39], v[52:55], 0
	v_add_f32_e64 v232, v232, v234
	v_add_f32_e64 v233, v233, v235
	v_mov_b32_e32 v234, 0
	v_mov_b32_e32 v235, 0
	v_mfma_f32_16x16x32_bf16 v[52:55], v[44:47], v[56:59], v[52:55]
	ds_read_b128 v[56:59], v214 offset:4608
	v_mov_b32_dpp v234, v232 row_mirror row_mask:0xf bank_mask:0xf
	v_mov_b32_dpp v235, v233 row_mirror row_mask:0xf bank_mask:0xf
	s_waitcnt lgkmcnt(0)
	v_mfma_f32_16x16x32_bf16 v[56:59], v[36:39], v[56:59], 0
	v_add_f32_e64 v232, v232, v234
	v_add_f32_e64 v233, v233, v235
	s_nop 0
	v_cndmask_b32_e32 v52, v143, v52, vcc
	v_pk_fma_f32 v[168:169], v[168:169], v[174:175], v[232:233]
	v_mfma_f32_16x16x32_bf16 v[56:59], v[44:47], v[60:63], v[56:59]
	ds_read_b128 v[60:63], v214 offset:6912
	ds_read_b128 v[172:175], v214 offset:6976
	v_cndmask_b32_e64 v53, v143, v53, s[10:11]
	s_waitcnt lgkmcnt(1)
	v_mfma_f32_16x16x32_bf16 v[60:63], v[36:39], v[60:63], 0
	v_cndmask_b32_e64 v54, v143, v54, s[16:17]
	v_cndmask_b32_e64 v55, v143, v55, s[24:25]
	v_mov_b32_e32 v234, 0
	s_waitcnt lgkmcnt(0)
	v_mfma_f32_16x16x32_bf16 v[60:63], v[44:47], v[172:175], v[60:63]
	v_add_u32_e32 v172, -3, v217
	v_cmp_lt_u32_e64 s[34:35], s57, v172
	v_cndmask_b32_e64 v173, v143, v56, s[8:9]
	v_mov_b32_e32 v235, 0
	v_cndmask_b32_e64 v48, v143, v48, s[34:35]
	v_max3_f32 v172, v48, s58, v52
	s_nop 1
	v_cndmask_b32_e64 v174, v143, v60, s[12:13]
	v_max3_f32 v56, v172, v173, v174
	v_mov_b32_e32 v60, 0
	v_cndmask_b32_e64 v175, v143, v61, s[18:19]
	v_mov_b32_e32 v61, 0
	v_mov_b32_dpp v60, v56 quad_perm:[1,0,3,2] row_mask:0xf bank_mask:0xf
	v_max_f32_e32 v60, v60, v60
	v_max_f32_e32 v56, v56, v60
	v_mov_b32_e32 v60, 0
	v_add_u32_e32 v214, 0x2400, v214
	s_nop 0
	v_mov_b32_dpp v60, v56 quad_perm:[2,3,0,1] row_mask:0xf bank_mask:0xf
	v_max_f32_e32 v60, v60, v60
	v_max_f32_e32 v56, v56, v60
	v_mov_b32_e32 v60, 0
	s_nop 1
	v_mov_b32_dpp v60, v56 row_half_mirror row_mask:0xf bank_mask:0xf
	v_max_f32_e32 v60, v60, v60
	v_max_f32_e32 v56, v56, v60
	v_mov_b32_e32 v60, 0
	s_nop 1
	v_mov_b32_dpp v60, v56 row_mirror row_mask:0xf bank_mask:0xf
	v_max3_f32 v221, v228, v56, v60
	v_sub_f32_e32 v48, v48, v221
	v_sub_f32_e32 v56, v228, v221
	v_exp_f32_e32 v60, v48
	v_sub_f32_e32 v48, v52, v221
	v_exp_f32_e32 v172, v56
	v_exp_f32_e32 v56, v48
	v_sub_f32_e32 v48, v173, v221
	v_add_u32_e32 v173, -2, v217
	v_cmp_lt_u32_e32 vcc, s57, v173
	v_exp_f32_e32 v52, v48
	v_sub_f32_e32 v48, v174, v221
	v_cndmask_b32_e32 v49, v143, v49, vcc
	v_max3_f32 v173, v49, s58, v53
	v_cndmask_b32_e64 v174, v143, v57, s[14:15]
	v_max3_f32 v57, v173, v174, v175
	v_exp_f32_e32 v48, v48
	v_mov_b32_e32 v228, v221
	v_mov_b32_dpp v61, v57 quad_perm:[1,0,3,2] row_mask:0xf bank_mask:0xf
	v_max_f32_e32 v61, v61, v61
	v_max_f32_e32 v57, v57, v61
	v_mov_b32_e32 v61, 0
	s_nop 1
	v_mov_b32_dpp v61, v57 quad_perm:[2,3,0,1] row_mask:0xf bank_mask:0xf
	v_max_f32_e32 v61, v61, v61
	v_max_f32_e32 v57, v57, v61
	v_mov_b32_e32 v61, 0
	s_nop 1
	v_mov_b32_dpp v61, v57 row_half_mirror row_mask:0xf bank_mask:0xf
	v_max_f32_e32 v61, v61, v61
	v_max_f32_e32 v57, v57, v61
	v_mov_b32_e32 v61, 0
	s_nop 1
	v_mov_b32_dpp v61, v57 row_mirror row_mask:0xf bank_mask:0xf
	v_max3_f32 v224, v226, v57, v61
	v_sub_f32_e32 v49, v49, v224
	v_sub_f32_e32 v57, v226, v224
	v_exp_f32_e32 v61, v49
	v_sub_f32_e32 v49, v53, v224
	v_exp_f32_e32 v173, v57
	v_exp_f32_e32 v57, v49
	v_sub_f32_e32 v49, v174, v224
	v_exp_f32_e32 v53, v49
	v_sub_f32_e32 v49, v175, v224
	v_exp_f32_e32 v49, v49
	v_pk_add_f32 v[174:175], v[60:61], 0 op_sel_hi:[1,0]
	v_mov_b32_e32 v226, 0
	v_pk_add_f32 v[174:175], v[56:57], v[174:175]
	v_cvt_pk_bf16_f32 v60, v60, s0
	v_pk_add_f32 v[174:175], v[52:53], v[174:175]
	v_cvt_pk_bf16_f32 v56, v56, s0
	v_pk_add_f32 v[174:175], v[48:49], v[174:175]
	v_cvt_pk_bf16_f32 v52, v52, s0
	v_cvt_pk_bf16_f32 v48, v48, s0
	v_mov_b32_dpp v226, v174 quad_perm:[1,0,3,2] row_mask:0xf bank_mask:0xf
	v_mov_b32_dpp v227, v175 quad_perm:[1,0,3,2] row_mask:0xf bank_mask:0xf
	v_pk_add_f32 v[174:175], v[174:175], v[226:227]
	v_mov_b32_e32 v226, 0
	v_mov_b32_e32 v227, 0
	ds_write_b16 v85, v60
	v_mov_b32_dpp v226, v174 quad_perm:[2,3,0,1] row_mask:0xf bank_mask:0xf
	v_mov_b32_dpp v227, v175 quad_perm:[2,3,0,1] row_mask:0xf bank_mask:0xf
	v_pk_add_f32 v[174:175], v[174:175], v[226:227]
	v_mov_b32_e32 v226, 0
	v_mov_b32_e32 v227, 0
	v_cvt_pk_bf16_f32 v60, v61, s0
	v_mov_b32_dpp v226, v174 row_half_mirror row_mask:0xf bank_mask:0xf
	v_mov_b32_dpp v227, v175 row_half_mirror row_mask:0xf bank_mask:0xf
	v_pk_add_f32 v[174:175], v[174:175], v[226:227]
	v_mov_b32_e32 v226, 0
	v_mov_b32_e32 v227, 0
	ds_write_b16 v85, v56 offset:32
	v_mov_b32_dpp v226, v174 row_mirror row_mask:0xf bank_mask:0xf
	v_mov_b32_dpp v227, v175 row_mirror row_mask:0xf bank_mask:0xf
	v_pk_add_f32 v[174:175], v[174:175], v[226:227]
	v_cndmask_b32_e64 v226, v143, v62, s[22:23]
	v_pk_fma_f32 v[166:167], v[166:167], v[172:173], v[174:175]
	v_add_u32_e32 v174, -1, v217
	v_cmp_lt_u32_e32 vcc, s57, v174
	v_cndmask_b32_e64 v175, v143, v58, s[20:21]
	v_mov_b32_e32 v62, 0
	v_cndmask_b32_e32 v50, v143, v50, vcc
	v_max3_f32 v174, v50, s58, v54
	v_max3_f32 v58, v174, v175, v226
	v_cmp_lt_u32_e32 vcc, s57, v217
	v_cndmask_b32_e64 v217, v143, v59, s[26:27]
	v_mov_b32_dpp v62, v58 quad_perm:[1,0,3,2] row_mask:0xf bank_mask:0xf
	v_max_f32_e32 v62, v62, v62
	v_max_f32_e32 v58, v58, v62
	v_mov_b32_e32 v62, 0
; #define LAS __attribute__((address_space(3)))
; __device__ __forceinline__ unsigned f2bf(float f) { return pk2(f, 0.f) & 0xffffu; }
; __device__ __forceinline__ float red16_sum(float x) { x = red8_sum(x); x += dppf<0x140>(x); return x; }
; #define LDS_WAIT() asm volatile("s_waitcnt lgkmcnt(0)" ::: "memory")
; __device__ __forceinline__ void attn_prompt_item(const Args& A, LAS unsigned char* lds, int tid, int lane, int wave, int b, int nb, int kvh) {
;     ...
;                 for (int j = 0; j < 4; ++j) {
;                     const int dq = kc * 64 + fr - (tt * 32 + mt * 16 + q4 * 4 + j) - 1;
;                     float mx = -1e30f;
; #pragma unroll
;                     for (int nt = 0; nt < 4; ++nt) { const bool ok = (unsigned)(dq + nt * 16) < 128u;
;                         const float s = ok ? S[nt][j] : -1e30f; S[nt][j] = s; mx = fmaxf(mx, s); }
;                     mx = red16_max(mx);
;                     const float mn = fmaxf(mrow[mt][j], mx); alpha[j] = __builtin_amdgcn_exp2f(mrow[mt][j] - mn); mrow[mt][j] = mn;
;                     float rs = 0.f;
; #pragma unroll
;                     for (int nt = 0; nt < 4; ++nt) { const float p = __builtin_amdgcn_exp2f(S[nt][j] - mn); S[nt][j] = p; rs += p; }
;                     rs = red16_sum(rs); lrow[mt][j] = lrow[mt][j] * alpha[j] + rs;
;                 }
; #pragma unroll
;                 for (int dt = 0; dt < 4; ++dt)
; #pragma unroll
;                     for (int j = 0; j < 4; ++j) O[mt][dt][j] *= alpha[j];
; #pragma unroll
;                 for (int nt = 0; nt < 4; ++nt)
; #pragma unroll
;                     for (int j = 0; j < 4; ++j) *(LAS unsigned short*)(Pw + (q4 * 4 + j) * 144 + (nt * 16 + fr) * 2) = (unsigned short)f2bf(S[nt][j]);
;                 LDS_WAIT();
;                 bf16x8 Pa[2];
; #pragma unroll
;                 for (int ks = 0; ks < 2; ++ks) Pa[ks] = *(const LAS bf16x8*)(Pw + fr * 144 + (ks * 32 + q4 * 8) * 2);
; #pragma unroll
;                 for (int dt = 0; dt < 4; ++dt)
; #pragma unroll
;                     for (int ks = 0; ks < 2; ++ks) { const bf16x8 Bv = *(const LAS bf16x8*)(lds + AT_V + (dt * 16 + fr) * 528 + (kc * 64 + ks * 32 + q4 * 8) * 2);
;                         O[mt][dt] = __builtin_amdgcn_mfma_f32_16x16x32_bf16(Pa[ks], Bv, O[mt][dt], 0, 0, 0); }
;                 LDS_WAIT();
;             }
	v_cndmask_b32_e32 v51, v143, v51, vcc
	v_cvt_pk_bf16_f32 v56, v57, s0
	v_mov_b32_dpp v62, v58 quad_perm:[2,3,0,1] row_mask:0xf bank_mask:0xf
	v_max_f32_e32 v62, v62, v62
	v_max_f32_e32 v58, v58, v62
	v_mov_b32_e32 v62, 0
	ds_write_b16 v85, v52 offset:64
	v_cvt_pk_bf16_f32 v52, v53, s0
	v_mov_b32_dpp v62, v58 row_half_mirror row_mask:0xf bank_mask:0xf
	v_max_f32_e32 v62, v62, v62
	v_max_f32_e32 v58, v58, v62
	v_mov_b32_e32 v62, 0
	ds_write_b16 v85, v48 offset:96
	v_cvt_pk_bf16_f32 v48, v49, s0
	v_mov_b32_dpp v62, v58 row_mirror row_mask:0xf bank_mask:0xf
	v_max3_f32 v227, v222, v58, v62
	v_sub_f32_e32 v50, v50, v227
	v_sub_f32_e32 v58, v222, v227
	v_exp_f32_e32 v62, v50
	v_sub_f32_e32 v50, v54, v227
	v_exp_f32_e32 v174, v58
	v_exp_f32_e32 v58, v50
	v_sub_f32_e32 v50, v175, v227
	v_max3_f32 v175, v51, s58, v55
	v_cndmask_b32_e64 v222, v143, v63, s[28:29]
	v_max3_f32 v59, v175, v217, v222
	v_mov_b32_e32 v63, 0
	v_exp_f32_e32 v54, v50
	v_sub_f32_e32 v50, v226, v227
	v_mov_b32_dpp v63, v59 quad_perm:[1,0,3,2] row_mask:0xf bank_mask:0xf
	v_max_f32_e32 v63, v63, v63
	v_max_f32_e32 v59, v59, v63
	v_mov_b32_e32 v63, 0
	v_exp_f32_e32 v50, v50
	ds_write_b16 v85, v60 offset:144
	v_mov_b32_dpp v63, v59 quad_perm:[2,3,0,1] row_mask:0xf bank_mask:0xf
	v_max_f32_e32 v63, v63, v63
	v_max_f32_e32 v59, v59, v63
	v_mov_b32_e32 v63, 0
	v_cvt_pk_bf16_f32 v60, v62, s0
	ds_write_b16 v85, v56 offset:176
	v_mov_b32_dpp v63, v59 row_half_mirror row_mask:0xf bank_mask:0xf
	v_max_f32_e32 v63, v63, v63
	v_max_f32_e32 v59, v59, v63
	v_mov_b32_e32 v63, 0
	v_cvt_pk_bf16_f32 v56, v58, s0
	ds_write_b16 v85, v52 offset:208
	v_mov_b32_dpp v63, v59 row_mirror row_mask:0xf bank_mask:0xf
	v_max3_f32 v229, v220, v59, v63
	v_sub_f32_e32 v51, v51, v229
	v_sub_f32_e32 v59, v220, v229
	v_exp_f32_e32 v63, v51
	v_sub_f32_e32 v51, v55, v229
	v_exp_f32_e32 v175, v59
	v_exp_f32_e32 v59, v51
	v_sub_f32_e32 v51, v217, v229
	v_exp_f32_e32 v55, v51
	v_sub_f32_e32 v51, v222, v229
	v_exp_f32_e32 v51, v51
	v_cvt_pk_bf16_f32 v52, v54, s0
	ds_write_b16 v85, v48 offset:240
	v_cvt_pk_bf16_f32 v48, v50, s0
	v_pk_add_f32 v[232:233], v[62:63], 0 op_sel_hi:[1,0]
	ds_write_b16 v85, v60 offset:288
	v_cvt_pk_bf16_f32 v60, v63, s0
	ds_write_b16 v85, v56 offset:320
	v_cvt_pk_bf16_f32 v56, v59, s0
	ds_write_b16 v85, v52 offset:352
	v_cvt_pk_bf16_f32 v52, v55, s0
	ds_write_b16 v85, v48 offset:384
	v_cvt_pk_bf16_f32 v48, v51, s0
	v_pk_add_f32 v[232:233], v[58:59], v[232:233]
	ds_write_b16 v85, v60 offset:432
	ds_write_b16 v85, v56 offset:464
	ds_write_b16 v85, v52 offset:496
	ds_write_b16 v85, v48 offset:528
	v_pk_add_f32 v[232:233], v[54:55], v[232:233]
	s_waitcnt lgkmcnt(0)
	v_pk_mul_f32 v[14:15], v[14:15], v[174:175]
	v_pk_add_f32 v[232:233], v[50:51], v[232:233]
	ds_read_b128 v[48:51], v91
	ds_read_b128 v[52:55], v91 offset:64
	ds_read_b128 v[56:59], v215
	v_pk_mul_f32 v[12:13], v[12:13], v[172:173]
	v_pk_mul_f32 v[10:11], v[10:11], v[174:175]
	v_pk_mul_f32 v[8:9], v[8:9], v[172:173]
	s_waitcnt lgkmcnt(0)
	v_mfma_f32_16x16x32_bf16 v[12:15], v[48:51], v[56:59], v[12:15]
	ds_read_b128 v[56:59], v215 offset:64
	v_pk_mul_f32 v[6:7], v[6:7], v[174:175]
	v_pk_mul_f32 v[4:5], v[4:5], v[172:173]
	s_waitcnt lgkmcnt(0)
	v_mfma_f32_16x16x32_bf16 v[12:15], v[52:55], v[56:59], v[12:15]
	ds_read_b128 v[56:59], v215 offset:8448
	v_pk_mul_f32 v[2:3], v[2:3], v[174:175]
	v_pk_mul_f32 v[0:1], v[0:1], v[172:173]
	s_waitcnt lgkmcnt(0)
	v_mfma_f32_16x16x32_bf16 v[8:11], v[48:51], v[56:59], v[8:11]
	ds_read_b128 v[56:59], v215 offset:8512
	v_mov_b32_dpp v234, v232 quad_perm:[1,0,3,2] row_mask:0xf bank_mask:0xf
	v_mov_b32_dpp v235, v233 quad_perm:[1,0,3,2] row_mask:0xf bank_mask:0xf
	s_waitcnt lgkmcnt(0)
	v_mfma_f32_16x16x32_bf16 v[8:11], v[52:55], v[56:59], v[8:11]
	ds_read_b128 v[56:59], v215 offset:16896
	v_pk_add_f32 v[232:233], v[232:233], v[234:235]
	v_mov_b32_e32 v234, 0
	s_waitcnt lgkmcnt(0)
	v_mfma_f32_16x16x32_bf16 v[4:7], v[48:51], v[56:59], v[4:7]
	ds_read_b128 v[56:59], v215 offset:16960
	v_mov_b32_e32 v235, 0
	v_mov_b32_dpp v234, v232 quad_perm:[2,3,0,1] row_mask:0xf bank_mask:0xf
	s_waitcnt lgkmcnt(0)
	v_mfma_f32_16x16x32_bf16 v[4:7], v[52:55], v[56:59], v[4:7]
	ds_read_b128 v[56:59], v216
	v_mov_b32_dpp v235, v233 quad_perm:[2,3,0,1] row_mask:0xf bank_mask:0xf
	v_pk_add_f32 v[232:233], v[232:233], v[234:235]
	s_waitcnt lgkmcnt(0)
	v_mfma_f32_16x16x32_bf16 v[0:3], v[48:51], v[56:59], v[0:3]
	ds_read_b128 v[48:51], v216 offset:64
	v_mov_b32_e32 v234, 0
	v_mov_b32_e32 v235, 0
	s_waitcnt lgkmcnt(0)
	v_mfma_f32_16x16x32_bf16 v[0:3], v[52:55], v[48:51], v[0:3]
	v_mov_b32_dpp v234, v232 row_half_mirror row_mask:0xf bank_mask:0xf
	v_mov_b32_dpp v235, v233 row_half_mirror row_mask:0xf bank_mask:0xf
	v_pk_add_f32 v[232:233], v[232:233], v[234:235]
	v_mov_b32_e32 v234, 0
	v_mov_b32_e32 v235, 0
	s_waitcnt lgkmcnt(0)
	v_add_u32_e32 v216, 0x80, v216
	v_mov_b32_dpp v234, v232 row_mirror row_mask:0xf bank_mask:0xf
	v_mov_b32_dpp v235, v233 row_mirror row_mask:0xf bank_mask:0xf
	v_pk_add_f32 v[232:233], v[232:233], v[234:235]
	v_add_u32_e32 v215, 0x80, v215
	v_pk_fma_f32 v[164:165], v[164:165], v[174:175], v[232:233]
	v_mov_b32_e32 v217, v230
	v_mov_b32_e32 v172, v218
	v_mov_b32_e32 v173, v219
	v_mov_b32_e32 v174, v223
	v_mov_b32_e32 v175, v225
	v_mov_b32_e32 v226, v224
	v_mov_b32_e32 v222, v227
	v_mov_b32_e32 v220, v229
	s_cbranch_scc0 .LBB0_314
; __device__ __forceinline__ unsigned f2bf(float f) { return pk2(f, 0.f) & 0xffffu; }
; __device__ __forceinline__ float siluf_(float x) { return x * __builtin_amdgcn_rcpf(1.f + __expf(-x)); }
; __device__ __forceinline__ void attn_prompt_item(const Args& A, LAS unsigned char* lds, int tid, int lane, int wave, int b, int nb, int kvh) {
;     ...
; #pragma unroll
;         for (int mt = 0; mt < 2; ++mt)
; #pragma unroll
;             for (int j = 0; j < 4; ++j) {
;                 const int tq = tt * 32 + mt * 16 + q4 * 4 + j; const size_t row = (size_t)b * SEQ + nb * 128 + tq; const float il = __builtin_amdgcn_rcpf(lrow[mt][j]);
; #pragma unroll
;                 for (int dt = 0; dt < 4; ++dt) { const int d = dt * 16 + fr; const float g = bf2f(gts[mt][j][dt]);
;                     MIX[row * DM + 512 + hq * 64 + d] = (bf16_t)f2bf(O[mt][dt][j] * il * siluf_(g)); }
	s_waitcnt lgkmcnt(0)
	v_lshrrev_b32_e64 v250, 2, s65
	v_lshl_add_u32 v250, v250, 7, v237
	v_add_u32_e32 v251, 0x4000, v250
	v_add_u32_e32 v252, 0x8000, v250
	v_add_u32_e32 v253, 0xc000, v250
	s_waitcnt vmcnt(31)
	v_lshlrev_b32_e32 v34, 16, v213
	v_mul_f32_e32 v32, 0xbfb8aa3b, v34
	v_exp_f32_e32 v32, v32
	s_waitcnt vmcnt(30)
	v_lshlrev_b32_e32 v37, 16, v111
	v_rcp_f32_e32 v36, v170
	s_add_u32 s8, s3, s42
	v_add_f32_e32 v32, 1.0, v32
	v_rcp_f32_e32 v35, v32
	v_mul_f32_e32 v28, v36, v28
	s_addc_u32 s9, s51, 0
	v_lshl_add_u64 v[32:33], s[8:9], 0, v[148:149]
	v_mul_f32_e32 v34, v35, v34
	v_mul_f32_e32 v35, 0xbfb8aa3b, v37
	v_exp_f32_e32 v35, v35
	v_mul_f32_e32 v28, v34, v28
	v_mov_b32_e32 v111, v67
	v_cvt_pk_bf16_f32 v28, v28, s0
	v_add_f32_e32 v34, 1.0, v35
	v_rcp_f32_e32 v38, v34
	v_lshl_add_u64 v[34:35], v[32:33], 0, v[110:111]
	ds_write_b16 v239, v28 offset:0
	v_mul_f32_e32 v24, v36, v24
	v_mul_f32_e32 v28, v38, v37
	s_waitcnt vmcnt(30)
	v_lshlrev_b32_e32 v37, 16, v212
	v_mul_f32_e32 v38, 0xbfb8aa3b, v37
	v_exp_f32_e32 v38, v38
	v_mul_f32_e32 v24, v28, v24
	v_cvt_pk_bf16_f32 v24, v24, s0
	ds_write_b16 v239, v24 offset:32
	v_add_f32_e32 v24, 1.0, v38
	s_waitcnt vmcnt(30)
	v_lshlrev_b32_e32 v28, 16, v89
	v_rcp_f32_e32 v24, v24
	v_mul_f32_e32 v38, 0xbfb8aa3b, v28
	v_exp_f32_e32 v38, v38
	v_mul_f32_e32 v20, v36, v20
	v_mul_f32_e32 v24, v24, v37
	v_mul_f32_e32 v20, v24, v20
	v_add_f32_e32 v24, 1.0, v38
	v_rcp_f32_e32 v24, v24
	v_cvt_pk_bf16_f32 v20, v20, s0
	ds_write_b16 v239, v20 offset:64
	v_mul_f32_e32 v16, v36, v16
	v_mul_f32_e32 v20, v24, v28
	s_waitcnt vmcnt(30)
	v_lshlrev_b32_e32 v24, 16, v211
	v_mul_f32_e32 v28, 0xbfb8aa3b, v24
	v_exp_f32_e32 v28, v28
	v_mul_f32_e32 v16, v20, v16
	v_rcp_f32_e32 v20, v171
	v_mov_b32_e32 v89, v67
	v_cvt_pk_bf16_f32 v16, v16, s0
	v_lshl_add_u64 v[32:33], v[32:33], 0, v[88:89]
	v_add_f32_e32 v28, 1.0, v28
	s_waitcnt vmcnt(29)
	v_lshlrev_b32_e32 v34, 16, v210
	ds_write_b16 v239, v16 offset:96
	v_mul_f32_e32 v16, v20, v29
	v_rcp_f32_e32 v28, v28
	v_mul_f32_e32 v29, 0xbfb8aa3b, v34
	v_exp_f32_e32 v29, v29
	v_lshl_add_u64 v[32:33], s[8:9], 0, v[150:151]
	v_mul_f32_e32 v24, v28, v24
	v_mul_f32_e32 v16, v24, v16
	v_add_f32_e32 v24, 1.0, v29
	v_rcp_f32_e32 v24, v24
	v_cvt_pk_bf16_f32 v16, v16, s0
	v_lshl_add_u64 v[28:29], v[32:33], 0, v[110:111]
	ds_write_b16 v239, v16 offset:144
	v_mul_f32_e32 v16, v20, v25
	s_waitcnt vmcnt(30)
	v_lshlrev_b32_e32 v25, 16, v203
	v_mul_f32_e32 v24, v24, v34
	v_mul_f32_e32 v34, 0xbfb8aa3b, v25
	v_exp_f32_e32 v34, v34
	v_mul_f32_e32 v16, v24, v16
	v_cvt_pk_bf16_f32 v16, v16, s0
	ds_write_b16 v239, v16 offset:176
	v_add_f32_e32 v16, 1.0, v34
	s_waitcnt vmcnt(30)
	v_lshlrev_b32_e32 v24, 16, v202
	v_rcp_f32_e32 v16, v16
	v_mul_f32_e32 v34, 0xbfb8aa3b, v24
	v_exp_f32_e32 v34, v34
	v_mul_f32_e32 v21, v20, v21
	v_mul_f32_e32 v16, v16, v25
	v_mul_f32_e32 v16, v16, v21
	v_add_f32_e32 v21, 1.0, v34
	v_rcp_f32_e32 v21, v21
	v_cvt_pk_bf16_f32 v16, v16, s0
	ds_write_b16 v239, v16 offset:208
	v_mul_f32_e32 v16, v20, v17
	v_mul_f32_e32 v17, v21, v24
	s_waitcnt vmcnt(30)
	v_lshlrev_b32_e32 v21, 16, v201
	v_mul_f32_e32 v25, 0xbfb8aa3b, v21
	v_exp_f32_e32 v25, v25
	v_rcp_f32_e32 v24, v168
	s_waitcnt vmcnt(29)
	v_lshlrev_b32_e32 v28, 16, v200
	v_mul_f32_e32 v29, 0xbfb8aa3b, v28
	v_add_f32_e32 v25, 1.0, v25
	v_rcp_f32_e32 v25, v25
	v_mul_f32_e32 v16, v17, v16
	v_exp_f32_e32 v29, v29
	v_cvt_pk_bf16_f32 v20, v16, s0
	v_lshl_add_u64 v[16:17], v[32:33], 0, v[88:89]
	ds_write_b16 v239, v20 offset:240
	v_mul_f32_e32 v20, v24, v30
	v_mul_f32_e32 v21, v25, v21
	v_mul_f32_e32 v20, v21, v20
	v_cvt_pk_bf16_f32 v25, v20, s0
	v_add_f32_e32 v20, 1.0, v29
	v_rcp_f32_e32 v29, v20
	v_lshl_add_u64 v[16:17], s[8:9], 0, v[152:153]
	v_lshl_add_u64 v[20:21], v[16:17], 0, v[110:111]
	ds_write_b16 v239, v25 offset:288
	v_mul_f32_e32 v25, v24, v26
	v_mul_f32_e32 v26, v29, v28
	s_waitcnt vmcnt(30)
	v_lshlrev_b32_e32 v28, 16, v199
	v_mul_f32_e32 v29, 0xbfb8aa3b, v28
	v_exp_f32_e32 v29, v29
	v_mul_f32_e32 v25, v26, v25
	v_cvt_pk_bf16_f32 v25, v25, s0
	ds_write_b16 v239, v25 offset:320
	v_add_f32_e32 v25, 1.0, v29
	s_waitcnt vmcnt(30)
	v_lshlrev_b32_e32 v26, 16, v198
	v_rcp_f32_e32 v25, v25
	v_mul_f32_e32 v29, 0xbfb8aa3b, v26
	v_exp_f32_e32 v29, v29
	v_mul_f32_e32 v22, v24, v22
	v_mul_f32_e32 v25, v25, v28
	v_mul_f32_e32 v22, v25, v22
	v_add_f32_e32 v25, 1.0, v29
	v_rcp_f32_e32 v25, v25
	v_cvt_pk_bf16_f32 v22, v22, s0
	ds_write_b16 v239, v22 offset:352
	v_mul_f32_e32 v18, v24, v18
	v_mul_f32_e32 v20, v25, v26
	v_mul_f32_e32 v18, v20, v18
	s_waitcnt vmcnt(30)
	v_lshlrev_b32_e32 v20, 16, v197
	v_mul_f32_e32 v21, 0xbfb8aa3b, v20
	v_exp_f32_e32 v21, v21
	s_waitcnt vmcnt(29)
	v_lshlrev_b32_e32 v24, 16, v196
	v_rcp_f32_e32 v22, v169
	v_mul_f32_e32 v25, 0xbfb8aa3b, v24
	v_add_f32_e32 v21, 1.0, v21
	v_rcp_f32_e32 v21, v21
	v_exp_f32_e32 v25, v25
	v_cvt_pk_bf16_f32 v18, v18, s0
	v_lshl_add_u64 v[16:17], v[16:17], 0, v[88:89]
	ds_write_b16 v239, v18 offset:384
	v_mul_f32_e32 v18, v22, v31
	v_mul_f32_e32 v20, v21, v20
	v_mul_f32_e32 v18, v20, v18
	v_add_f32_e32 v20, 1.0, v25
	v_rcp_f32_e32 v25, v20
	v_lshl_add_u64 v[16:17], s[8:9], 0, v[154:155]
	v_cvt_pk_bf16_f32 v18, v18, s0
	v_lshl_add_u64 v[20:21], v[16:17], 0, v[110:111]
	v_mul_f32_e32 v24, v25, v24
	s_waitcnt vmcnt(29)
	v_lshlrev_b32_e32 v25, 16, v195
	v_mul_f32_e32 v26, 0xbfb8aa3b, v25
	v_exp_f32_e32 v26, v26
	ds_write_b16 v239, v18 offset:432
	v_mul_f32_e32 v18, v22, v27
	v_mul_f32_e32 v18, v24, v18
	v_cvt_pk_bf16_f32 v18, v18, s0
	ds_write_b16 v239, v18 offset:464
	v_add_f32_e32 v18, 1.0, v26
	s_waitcnt vmcnt(30)
; __device__ __forceinline__ unsigned f2bf(float f) { return pk2(f, 0.f) & 0xffffu; }
; __device__ __forceinline__ float siluf_(float x) { return x * __builtin_amdgcn_rcpf(1.f + __expf(-x)); }
; __device__ __forceinline__ void attn_prompt_item(const Args& A, LAS unsigned char* lds, int tid, int lane, int wave, int b, int nb, int kvh) {
;     ...
; #pragma unroll
;         for (int mt = 0; mt < 2; ++mt)
; #pragma unroll
;             for (int j = 0; j < 4; ++j) {
;                 const int tq = tt * 32 + mt * 16 + q4 * 4 + j; const size_t row = (size_t)b * SEQ + nb * 128 + tq; const float il = __builtin_amdgcn_rcpf(lrow[mt][j]);
; #pragma unroll
;                 for (int dt = 0; dt < 4; ++dt) { const int d = dt * 16 + fr; const float g = bf2f(gts[mt][j][dt]);
;                     MIX[row * DM + 512 + hq * 64 + d] = (bf16_t)f2bf(O[mt][dt][j] * il * siluf_(g)); }
	v_lshlrev_b32_e32 v24, 16, v194
	v_rcp_f32_e32 v18, v18
	v_mul_f32_e32 v26, 0xbfb8aa3b, v24
	v_exp_f32_e32 v26, v26
	v_mul_f32_e32 v23, v22, v23
	v_mul_f32_e32 v18, v18, v25
	v_mul_f32_e32 v18, v18, v23
	v_add_f32_e32 v23, 1.0, v26
	v_rcp_f32_e32 v23, v23
	v_cvt_pk_bf16_f32 v18, v18, s0
	ds_write_b16 v239, v18 offset:496
	v_mul_f32_e32 v18, v22, v19
	v_mul_f32_e32 v19, v23, v24
	v_mul_f32_e32 v18, v19, v18
	s_waitcnt vmcnt(30)
	v_lshlrev_b32_e32 v19, 16, v193
	v_mul_f32_e32 v21, 0xbfb8aa3b, v19
	v_exp_f32_e32 v21, v21
	v_cvt_pk_bf16_f32 v18, v18, s0
	v_lshl_add_u64 v[16:17], v[16:17], 0, v[88:89]
	ds_write_b16 v239, v18 offset:528
	v_add_f32_e32 v18, 1.0, v21
	s_waitcnt vmcnt(30)
	v_lshlrev_b32_e32 v21, 16, v192
	v_rcp_f32_e32 v20, v166
	v_rcp_f32_e32 v18, v18
	v_mul_f32_e32 v22, 0xbfb8aa3b, v21
	v_exp_f32_e32 v22, v22
	v_mul_f32_e32 v12, v20, v12
	v_mul_f32_e32 v18, v18, v19
	v_mul_f32_e32 v12, v18, v12
	v_add_f32_e32 v18, 1.0, v22
	v_rcp_f32_e32 v22, v18
	v_lshl_add_u64 v[16:17], s[8:9], 0, v[156:157]
	v_cvt_pk_bf16_f32 v12, v12, s0
	v_lshl_add_u64 v[18:19], v[16:17], 0, v[110:111]
	ds_write_b16 v239, v12 offset:2304
	v_mul_f32_e32 v12, v22, v21
	s_waitcnt vmcnt(30)
	v_lshlrev_b32_e32 v21, 16, v191
	v_mul_f32_e32 v22, 0xbfb8aa3b, v21
	v_exp_f32_e32 v22, v22
	v_mul_f32_e32 v8, v20, v8
	v_mul_f32_e32 v8, v12, v8
	v_cvt_pk_bf16_f32 v8, v8, s0
	ds_write_b16 v239, v8 offset:2336
	v_add_f32_e32 v8, 1.0, v22
	s_waitcnt vmcnt(30)
	v_lshlrev_b32_e32 v12, 16, v190
	v_rcp_f32_e32 v8, v8
	v_mul_f32_e32 v22, 0xbfb8aa3b, v12
	v_exp_f32_e32 v22, v22
	v_mul_f32_e32 v4, v20, v4
	v_mul_f32_e32 v8, v8, v21
	v_mul_f32_e32 v4, v8, v4
	v_add_f32_e32 v8, 1.0, v22
	v_rcp_f32_e32 v8, v8
	v_cvt_pk_bf16_f32 v4, v4, s0
	ds_write_b16 v239, v4 offset:2368
	v_mul_f32_e32 v0, v20, v0
	v_mul_f32_e32 v4, v8, v12
	s_waitcnt vmcnt(30)
	v_lshlrev_b32_e32 v8, 16, v189
	v_mul_f32_e32 v12, 0xbfb8aa3b, v8
	v_exp_f32_e32 v12, v12
	v_mul_f32_e32 v0, v4, v0
	v_rcp_f32_e32 v4, v167
	v_cvt_pk_bf16_f32 v0, v0, s0
	v_lshl_add_u64 v[16:17], v[16:17], 0, v[88:89]
	v_add_f32_e32 v12, 1.0, v12
	s_waitcnt vmcnt(29)
	v_lshlrev_b32_e32 v18, 16, v188
	ds_write_b16 v239, v0 offset:2400
	v_mul_f32_e32 v0, v4, v13
	v_rcp_f32_e32 v12, v12
	v_mul_f32_e32 v13, 0xbfb8aa3b, v18
	v_exp_f32_e32 v13, v13
	v_lshl_add_u64 v[16:17], s[8:9], 0, v[158:159]
	v_mul_f32_e32 v8, v12, v8
	v_mul_f32_e32 v0, v8, v0
	v_add_f32_e32 v8, 1.0, v13
	v_rcp_f32_e32 v8, v8
	v_cvt_pk_bf16_f32 v0, v0, s0
	v_lshl_add_u64 v[12:13], v[16:17], 0, v[110:111]
	ds_write_b16 v239, v0 offset:2448
	v_mul_f32_e32 v0, v4, v9
	s_waitcnt vmcnt(30)
	v_lshlrev_b32_e32 v9, 16, v187
	v_mul_f32_e32 v8, v8, v18
	v_mul_f32_e32 v18, 0xbfb8aa3b, v9
	v_exp_f32_e32 v18, v18
	v_mul_f32_e32 v0, v8, v0
	v_cvt_pk_bf16_f32 v0, v0, s0
	ds_write_b16 v239, v0 offset:2480
	v_add_f32_e32 v0, 1.0, v18
	s_waitcnt vmcnt(30)
	v_lshlrev_b32_e32 v8, 16, v186
	v_rcp_f32_e32 v0, v0
	v_mul_f32_e32 v18, 0xbfb8aa3b, v8
	v_exp_f32_e32 v18, v18
	v_mul_f32_e32 v5, v4, v5
	v_mul_f32_e32 v0, v0, v9
	v_mul_f32_e32 v0, v0, v5
	v_add_f32_e32 v5, 1.0, v18
	v_rcp_f32_e32 v5, v5
	v_cvt_pk_bf16_f32 v0, v0, s0
	ds_write_b16 v239, v0 offset:2512
	v_mul_f32_e32 v0, v4, v1
	v_mul_f32_e32 v1, v5, v8
	s_waitcnt vmcnt(30)
	v_lshlrev_b32_e32 v5, 16, v185
	v_mul_f32_e32 v9, 0xbfb8aa3b, v5
	v_exp_f32_e32 v9, v9
	v_rcp_f32_e32 v8, v164
	s_waitcnt vmcnt(29)
	v_lshlrev_b32_e32 v12, 16, v184
	v_mul_f32_e32 v13, 0xbfb8aa3b, v12
	v_add_f32_e32 v9, 1.0, v9
	v_rcp_f32_e32 v9, v9
	v_mul_f32_e32 v0, v1, v0
	v_exp_f32_e32 v13, v13
	v_cvt_pk_bf16_f32 v4, v0, s0
	v_lshl_add_u64 v[0:1], v[16:17], 0, v[88:89]
	ds_write_b16 v239, v4 offset:2544
	v_mul_f32_e32 v4, v8, v14
	v_mul_f32_e32 v5, v9, v5
	v_mul_f32_e32 v4, v5, v4
	v_cvt_pk_bf16_f32 v9, v4, s0
	v_add_f32_e32 v4, 1.0, v13
	v_rcp_f32_e32 v13, v4
	v_lshl_add_u64 v[0:1], s[8:9], 0, v[160:161]
	v_lshl_add_u64 v[4:5], v[0:1], 0, v[110:111]
	ds_write_b16 v239, v9 offset:2592
	v_mul_f32_e32 v9, v8, v10
	v_mul_f32_e32 v10, v13, v12
	s_waitcnt vmcnt(30)
	v_lshlrev_b32_e32 v12, 16, v183
	v_mul_f32_e32 v13, 0xbfb8aa3b, v12
	v_exp_f32_e32 v13, v13
	v_mul_f32_e32 v9, v10, v9
	v_cvt_pk_bf16_f32 v9, v9, s0
	ds_write_b16 v239, v9 offset:2624
	v_add_f32_e32 v9, 1.0, v13
	s_waitcnt vmcnt(30)
	v_lshlrev_b32_e32 v10, 16, v182
	v_rcp_f32_e32 v9, v9
	v_mul_f32_e32 v13, 0xbfb8aa3b, v10
	v_exp_f32_e32 v13, v13
	v_mul_f32_e32 v6, v8, v6
	v_mul_f32_e32 v9, v9, v12
	v_mul_f32_e32 v6, v9, v6
	v_add_f32_e32 v9, 1.0, v13
	v_rcp_f32_e32 v9, v9
	v_cvt_pk_bf16_f32 v6, v6, s0
	ds_write_b16 v239, v6 offset:2656
	v_mul_f32_e32 v2, v8, v2
	v_mul_f32_e32 v4, v9, v10
	v_mul_f32_e32 v2, v4, v2
	s_waitcnt vmcnt(30)
	v_lshlrev_b32_e32 v4, 16, v181
	v_mul_f32_e32 v5, 0xbfb8aa3b, v4
	v_exp_f32_e32 v5, v5
	s_waitcnt vmcnt(29)
	v_lshlrev_b32_e32 v8, 16, v180
	v_rcp_f32_e32 v6, v165
	v_mul_f32_e32 v9, 0xbfb8aa3b, v8
	v_add_f32_e32 v5, 1.0, v5
	v_rcp_f32_e32 v5, v5
	v_exp_f32_e32 v9, v9
	v_cvt_pk_bf16_f32 v2, v2, s0
	v_lshl_add_u64 v[0:1], v[0:1], 0, v[88:89]
	ds_write_b16 v239, v2 offset:2688
	v_mul_f32_e32 v2, v6, v15
	v_mul_f32_e32 v4, v5, v4
	v_mul_f32_e32 v2, v4, v2
	v_add_f32_e32 v4, 1.0, v9
	v_rcp_f32_e32 v9, v4
	v_lshl_add_u64 v[0:1], s[8:9], 0, v[162:163]
	v_cvt_pk_bf16_f32 v2, v2, s0
	v_lshl_add_u64 v[4:5], v[0:1], 0, v[110:111]
	v_mul_f32_e32 v8, v9, v8
	s_waitcnt vmcnt(29)
	v_lshlrev_b32_e32 v9, 16, v179
	v_mul_f32_e32 v10, 0xbfb8aa3b, v9
	v_exp_f32_e32 v10, v10
	ds_write_b16 v239, v2 offset:2736
	v_mul_f32_e32 v2, v6, v11
	v_mul_f32_e32 v2, v8, v2
	v_cvt_pk_bf16_f32 v2, v2, s0
	ds_write_b16 v239, v2 offset:2768
	v_add_f32_e32 v2, 1.0, v10
	s_waitcnt vmcnt(30)
	v_lshlrev_b32_e32 v8, 16, v66
	v_rcp_f32_e32 v2, v2
	v_mul_f32_e32 v10, 0xbfb8aa3b, v8
	v_exp_f32_e32 v10, v10
	v_mul_f32_e32 v7, v6, v7
	v_mul_f32_e32 v2, v2, v9
	v_mul_f32_e32 v2, v2, v7
	v_add_f32_e32 v7, 1.0, v10
	v_rcp_f32_e32 v7, v7
	v_cvt_pk_bf16_f32 v2, v2, s0
	ds_write_b16 v239, v2 offset:2800
	v_mul_f32_e32 v2, v6, v3
	v_mul_f32_e32 v3, v7, v8
	v_mul_f32_e32 v2, v3, v2
	s_add_i32 s8, s65, 8
	v_cvt_pk_bf16_f32 v2, v2, s0
	v_lshl_add_u64 v[0:1], v[0:1], 0, v[88:89]
	s_cmp_gt_u32 s65, 7
	s_mov_b32 s65, s8
	ds_write_b16 v239, v2 offset:2832
	s_waitcnt lgkmcnt(0)
	ds_read_b128 v[180:183], v238
	ds_read_b128 v[184:187], v238 offset:1152
	ds_read_b128 v[188:191], v238 offset:2304
	ds_read_b128 v[192:195], v238 offset:3456
	s_waitcnt lgkmcnt(0)
	global_store_dwordx4 v250, v[180:183], s[100:101]
	global_store_dwordx4 v251, v[184:187], s[100:101]
	global_store_dwordx4 v252, v[188:191], s[100:101]
	global_store_dwordx4 v253, v[192:195], s[100:101]
	s_cbranch_scc0 .LBB0_307
	s_branch .LBB0_288
